# prep phase: p->bf16 loop unrolled x16 with loads batched ahead of stores; w_in/w_pg transposes issue all 8 row loads + scale loads before one wait
# speedup vs baseline: 1.0201x; 1.0201x over previous
.LBB0_8:
	s_or_b64 exec, exec, s[6:7]
	s_mov_b32 s0, 0x10000
	v_cmp_gt_i32_e32 vcc, s0, v2
	s_and_saveexec_b64 s[0:1], vcc
	s_cbranch_execz .LBB0_11
	v_ashrrev_i32_e32 v3, 31, v2
	v_lshlrev_b64 v[6:7], 9, v[2:3]
	v_lshlrev_b64 v[4:5], 10, v[2:3]
	v_lshl_or_b32 v6, v158, 3, v6
	v_lshl_or_b32 v4, v158, 4, v4
	s_ashr_i32 s5, s4, 31
	v_lshl_add_u64 v[6:7], s[80:81], 0, v[6:7]
	s_mov_b64 s[2:3], 0x34000000
	v_lshl_add_u64 v[4:5], s[54:55], 0, v[4:5]
	s_lshl_b64 s[6:7], s[4:5], 10
	v_lshl_add_u64 v[6:7], v[6:7], 0, s[2:3]
	s_lshl_b64 s[16:17], s[4:5], 9
	s_mov_b64 s[18:19], 0
	s_mov_b32 s2, 0xffff
	s_mul_i32 s3, s4, 15
	s_lshl_b32 s5, s4, 4
.Lmy_p16_top:
	v_add_u32_e32 v3, s3, v2
	v_cmp_ge_i32_e32 vcc, s2, v3
	s_cbranch_vccz .Lmy_p16_done
	global_load_dwordx4 v[50:53], v[4:5], off
	v_lshl_add_u64 v[4:5], v[4:5], 0, s[6:7]
	global_load_dwordx4 v[54:57], v[4:5], off
	v_lshl_add_u64 v[4:5], v[4:5], 0, s[6:7]
	global_load_dwordx4 v[58:61], v[4:5], off
	v_lshl_add_u64 v[4:5], v[4:5], 0, s[6:7]
	global_load_dwordx4 v[62:65], v[4:5], off
	v_lshl_add_u64 v[4:5], v[4:5], 0, s[6:7]
	global_load_dwordx4 v[66:69], v[4:5], off
	v_lshl_add_u64 v[4:5], v[4:5], 0, s[6:7]
	global_load_dwordx4 v[70:73], v[4:5], off
	v_lshl_add_u64 v[4:5], v[4:5], 0, s[6:7]
	global_load_dwordx4 v[74:77], v[4:5], off
	v_lshl_add_u64 v[4:5], v[4:5], 0, s[6:7]
	global_load_dwordx4 v[78:81], v[4:5], off
	v_lshl_add_u64 v[4:5], v[4:5], 0, s[6:7]
	global_load_dwordx4 v[82:85], v[4:5], off
	v_lshl_add_u64 v[4:5], v[4:5], 0, s[6:7]
	global_load_dwordx4 v[86:89], v[4:5], off
	v_lshl_add_u64 v[4:5], v[4:5], 0, s[6:7]
	global_load_dwordx4 v[90:93], v[4:5], off
	v_lshl_add_u64 v[4:5], v[4:5], 0, s[6:7]
	global_load_dwordx4 v[94:97], v[4:5], off
	v_lshl_add_u64 v[4:5], v[4:5], 0, s[6:7]
	global_load_dwordx4 v[98:101], v[4:5], off
	v_lshl_add_u64 v[4:5], v[4:5], 0, s[6:7]
	global_load_dwordx4 v[102:105], v[4:5], off
	v_lshl_add_u64 v[4:5], v[4:5], 0, s[6:7]
	global_load_dwordx4 v[106:109], v[4:5], off
	v_lshl_add_u64 v[4:5], v[4:5], 0, s[6:7]
	global_load_dwordx4 v[110:113], v[4:5], off
	v_lshl_add_u64 v[4:5], v[4:5], 0, s[6:7]
	v_add_u32_e32 v2, s5, v2
	s_waitcnt vmcnt(15)
	v_cvt_pk_bf16_f32 v50, v50, v51
	v_cvt_pk_bf16_f32 v51, v52, v53
	global_store_dwordx2 v[6:7], v[50:51], off
	v_lshl_add_u64 v[6:7], v[6:7], 0, s[16:17]
	s_waitcnt vmcnt(15)
	v_cvt_pk_bf16_f32 v54, v54, v55
	v_cvt_pk_bf16_f32 v55, v56, v57
	global_store_dwordx2 v[6:7], v[54:55], off
	v_lshl_add_u64 v[6:7], v[6:7], 0, s[16:17]
	s_waitcnt vmcnt(15)
	v_cvt_pk_bf16_f32 v58, v58, v59
	v_cvt_pk_bf16_f32 v59, v60, v61
	global_store_dwordx2 v[6:7], v[58:59], off
	v_lshl_add_u64 v[6:7], v[6:7], 0, s[16:17]
	s_waitcnt vmcnt(15)
	v_cvt_pk_bf16_f32 v62, v62, v63
	v_cvt_pk_bf16_f32 v63, v64, v65
	global_store_dwordx2 v[6:7], v[62:63], off
	v_lshl_add_u64 v[6:7], v[6:7], 0, s[16:17]
	s_waitcnt vmcnt(15)
	v_cvt_pk_bf16_f32 v66, v66, v67
	v_cvt_pk_bf16_f32 v67, v68, v69
	global_store_dwordx2 v[6:7], v[66:67], off
	v_lshl_add_u64 v[6:7], v[6:7], 0, s[16:17]
	s_waitcnt vmcnt(15)
	v_cvt_pk_bf16_f32 v70, v70, v71
	v_cvt_pk_bf16_f32 v71, v72, v73
	global_store_dwordx2 v[6:7], v[70:71], off
	v_lshl_add_u64 v[6:7], v[6:7], 0, s[16:17]
	s_waitcnt vmcnt(15)
	v_cvt_pk_bf16_f32 v74, v74, v75
	v_cvt_pk_bf16_f32 v75, v76, v77
	global_store_dwordx2 v[6:7], v[74:75], off
	v_lshl_add_u64 v[6:7], v[6:7], 0, s[16:17]
	s_waitcnt vmcnt(15)
	v_cvt_pk_bf16_f32 v78, v78, v79
	v_cvt_pk_bf16_f32 v79, v80, v81
	global_store_dwordx2 v[6:7], v[78:79], off
	v_lshl_add_u64 v[6:7], v[6:7], 0, s[16:17]
	s_waitcnt vmcnt(15)
	v_cvt_pk_bf16_f32 v82, v82, v83
	v_cvt_pk_bf16_f32 v83, v84, v85
	global_store_dwordx2 v[6:7], v[82:83], off
	v_lshl_add_u64 v[6:7], v[6:7], 0, s[16:17]
	s_waitcnt vmcnt(15)
	v_cvt_pk_bf16_f32 v86, v86, v87
	v_cvt_pk_bf16_f32 v87, v88, v89
	global_store_dwordx2 v[6:7], v[86:87], off
	v_lshl_add_u64 v[6:7], v[6:7], 0, s[16:17]
	s_waitcnt vmcnt(15)
	v_cvt_pk_bf16_f32 v90, v90, v91
	v_cvt_pk_bf16_f32 v91, v92, v93
	global_store_dwordx2 v[6:7], v[90:91], off
	v_lshl_add_u64 v[6:7], v[6:7], 0, s[16:17]
	s_waitcnt vmcnt(15)
	v_cvt_pk_bf16_f32 v94, v94, v95
	v_cvt_pk_bf16_f32 v95, v96, v97
	global_store_dwordx2 v[6:7], v[94:95], off
	v_lshl_add_u64 v[6:7], v[6:7], 0, s[16:17]
	s_waitcnt vmcnt(15)
	v_cvt_pk_bf16_f32 v98, v98, v99
	v_cvt_pk_bf16_f32 v99, v100, v101
	global_store_dwordx2 v[6:7], v[98:99], off
	v_lshl_add_u64 v[6:7], v[6:7], 0, s[16:17]
	s_waitcnt vmcnt(15)
	v_cvt_pk_bf16_f32 v102, v102, v103
	v_cvt_pk_bf16_f32 v103, v104, v105
	global_store_dwordx2 v[6:7], v[102:103], off
	v_lshl_add_u64 v[6:7], v[6:7], 0, s[16:17]
	s_waitcnt vmcnt(15)
	v_cvt_pk_bf16_f32 v106, v106, v107
	v_cvt_pk_bf16_f32 v107, v108, v109
	global_store_dwordx2 v[6:7], v[106:107], off
	v_lshl_add_u64 v[6:7], v[6:7], 0, s[16:17]
	s_waitcnt vmcnt(15)
	v_cvt_pk_bf16_f32 v110, v110, v111
	v_cvt_pk_bf16_f32 v111, v112, v113
	global_store_dwordx2 v[6:7], v[110:111], off
	v_lshl_add_u64 v[6:7], v[6:7], 0, s[16:17]
	s_branch .Lmy_p16_top
.Lmy_p16_done:
	v_cmp_ge_i32_e32 vcc, s2, v2
	s_cbranch_vccz .LBB0_11

.LBB0_11:
	s_or_b64 exec, exec, s[0:1]
	s_lshl_b32 s0, s82, 9
	v_lshl_or_b32 v10, s86, 9, v0
	s_add_u32 s16, s80, 0x36000000
	s_mov_b32 s1, 0x90000
	s_addc_u32 s17, s81, 0
	v_cmp_gt_i32_e32 vcc, s1, v10
	s_and_saveexec_b64 s[6:7], vcc
	s_cbranch_execz .LBB0_30
	s_cmp_lg_u64 s[56:57], 0
	s_cbranch_scc1 .Lmy_w1_fast
	s_cselect_b64 s[2:3], -1, 0
	v_cndmask_b32_e64 v1, 0, 1, s[2:3]
	s_mov_b64 s[18:19], 0
	s_mov_b32 s1, 0x38e38e39
	v_cmp_ne_u32_e64 s[4:5], 1, v1
	s_mov_b32 s2, 0x8ffff
	v_mov_b32_e32 v9, v10
	s_branch .LBB0_14

.Lmy_w1_fast:
	s_mov_b64 s[18:19], 0
	s_mov_b32 s1, 0x38e38e39
	s_mov_b32 s2, 0x8ffff
	s_mov_b32 s28, 0x4800
	s_mov_b32 s29, 0
	v_mov_b32_e32 v9, v10
.Lmy_w1_loop:
	v_mul_hi_i32 v1, v9, s1
	v_lshrrev_b32_e32 v2, 31, v1
	v_ashrrev_i32_e32 v1, 10, v1
	v_add_u32_e32 v1, v1, v2
	v_mul_i32_i24_e32 v2, 0x1200, v1
	v_sub_u32_e32 v14, v9, v2
	v_lshlrev_b32_e32 v12, 3, v1
	v_ashrrev_i32_e32 v15, 31, v14
	v_ashrrev_i32_e32 v13, 31, v12
	v_lshl_add_u64 v[16:17], v[14:15], 2, s[58:59]
	v_mul_hi_i32_i24_e32 v3, 0x4800, v12
	v_mul_i32_i24_e32 v2, 0x4800, v12
	v_lshl_add_u64 v[2:3], v[16:17], 0, v[2:3]
	v_lshl_add_u64 v[18:19], v[12:13], 2, s[56:57]
	global_load_dword v26, v[2:3], off
	v_lshl_add_u64 v[2:3], v[2:3], 0, s[28:29]
	global_load_dword v27, v[2:3], off
	v_lshl_add_u64 v[2:3], v[2:3], 0, s[28:29]
	global_load_dword v28, v[2:3], off
	v_lshl_add_u64 v[2:3], v[2:3], 0, s[28:29]
	global_load_dword v29, v[2:3], off
	v_lshl_add_u64 v[2:3], v[2:3], 0, s[28:29]
	global_load_dword v30, v[2:3], off
	v_lshl_add_u64 v[2:3], v[2:3], 0, s[28:29]
	global_load_dword v31, v[2:3], off
	v_lshl_add_u64 v[2:3], v[2:3], 0, s[28:29]
	global_load_dword v32, v[2:3], off
	v_lshl_add_u64 v[2:3], v[2:3], 0, s[28:29]
	global_load_dword v33, v[2:3], off
	global_load_dwordx4 v[34:37], v[18:19], off
	global_load_dwordx4 v[38:41], v[18:19], off offset:16
	v_lshlrev_b64 v[6:7], 11, v[14:15]
	v_add_u32_e32 v9, s0, v9
	v_lshl_add_u64 v[6:7], s[16:17], 0, v[6:7]
	v_cmp_lt_i32_e32 vcc, s2, v9
	v_lshl_add_u64 v[6:7], v[12:13], 1, v[6:7]
	s_or_b64 s[18:19], vcc, s[18:19]
	s_waitcnt vmcnt(0)
	v_mul_f32_e32 v26, v26, v34
	v_mul_f32_e32 v27, v27, v35
	v_mul_f32_e32 v28, v28, v36
	v_mul_f32_e32 v29, v29, v37
	v_mul_f32_e32 v30, v30, v38
	v_mul_f32_e32 v31, v31, v39
	v_mul_f32_e32 v32, v32, v40
	v_mul_f32_e32 v33, v33, v41
	v_cvt_pk_bf16_f32 v2, v26, v27
	v_cvt_pk_bf16_f32 v3, v28, v29
	v_cvt_pk_bf16_f32 v4, v30, v31
	v_cvt_pk_bf16_f32 v5, v32, v33
	global_store_dwordx4 v[6:7], v[2:5], off
	s_andn2_b64 exec, exec, s[18:19]
	s_cbranch_execnz .Lmy_w1_loop
	s_branch .LBB0_30

.LBB0_32:
	v_ashrrev_i32_e32 v2, 31, v1
	v_lshrrev_b32_e32 v2, 22, v2
	v_add_u32_e32 v2, v1, v2
	v_ashrrev_i32_e32 v2, 10, v2
	v_mul_i32_i24_e32 v3, 0x400, v2
	v_lshlrev_b32_e32 v2, 3, v2
	v_sub_u32_e32 v4, v1, v3
	v_ashrrev_i32_e32 v3, 31, v2
	v_or_b32_e32 v6, 1, v2
	v_or_b32_e32 v8, 2, v2
	v_or_b32_e32 v12, 3, v2
	v_or_b32_e32 v14, 4, v2
	v_or_b32_e32 v16, 5, v2
	v_or_b32_e32 v18, 6, v2
	v_or_b32_e32 v20, 7, v2
	v_ashrrev_i32_e32 v5, 31, v4
	v_lshlrev_b64 v[22:23], 12, v[2:3]
	v_ashrrev_i32_e32 v7, 31, v6
	v_ashrrev_i32_e32 v9, 31, v8
	v_ashrrev_i32_e32 v13, 31, v12
	v_ashrrev_i32_e32 v15, 31, v14
	v_ashrrev_i32_e32 v17, 31, v16
	v_ashrrev_i32_e32 v19, 31, v18
	v_ashrrev_i32_e32 v21, 31, v20
	v_lshl_add_u64 v[24:25], v[4:5], 2, s[8:9]
	v_lshlrev_b64 v[6:7], 12, v[6:7]
	v_lshlrev_b64 v[8:9], 12, v[8:9]
	v_lshlrev_b64 v[12:13], 12, v[12:13]
	v_lshlrev_b64 v[14:15], 12, v[14:15]
	v_lshlrev_b64 v[16:17], 12, v[16:17]
	v_lshlrev_b64 v[18:19], 12, v[18:19]
	v_lshlrev_b64 v[20:21], 12, v[20:21]
	v_lshl_add_u64 v[22:23], v[24:25], 0, v[22:23]
	v_lshl_add_u64 v[6:7], v[24:25], 0, v[6:7]
	v_lshl_add_u64 v[8:9], v[24:25], 0, v[8:9]
	v_lshl_add_u64 v[12:13], v[24:25], 0, v[12:13]
	v_lshl_add_u64 v[14:15], v[24:25], 0, v[14:15]
	v_lshl_add_u64 v[16:17], v[24:25], 0, v[16:17]
	v_lshl_add_u64 v[18:19], v[24:25], 0, v[18:19]
	v_lshl_add_u64 v[20:21], v[24:25], 0, v[20:21]
	global_load_dword v11, v[22:23], off
	global_load_dword v24, v[6:7], off
	global_load_dword v25, v[8:9], off
	global_load_dword v26, v[12:13], off
	global_load_dword v27, v[14:15], off
	global_load_dword v28, v[16:17], off
	global_load_dword v29, v[18:19], off
	global_load_dword v30, v[20:21], off
	v_add_u32_e32 v1, s0, v1
	v_lshlrev_b64 v[4:5], 11, v[4:5]
	v_cmp_lt_i32_e32 vcc, s1, v1
	v_lshl_add_u64 v[4:5], s[88:89], 0, v[4:5]
	s_or_b64 s[4:5], vcc, s[4:5]
	v_lshl_add_u64 v[6:7], v[2:3], 1, v[4:5]
	s_waitcnt vmcnt(6)
	v_cvt_pk_bf16_f32 v2, v11, v24
	s_waitcnt vmcnt(4)
	v_cvt_pk_bf16_f32 v3, v25, v26
	s_waitcnt vmcnt(2)
	v_cvt_pk_bf16_f32 v4, v27, v28
	s_waitcnt vmcnt(0)
	v_cvt_pk_bf16_f32 v5, v29, v30
	global_store_dwordx4 v[6:7], v[2:5], off
	s_andn2_b64 exec, exec, s[4:5]
	s_cbranch_execnz .LBB0_32
	s_or_b64 exec, exec, s[4:5]
	s_add_u32 s8, s80, 0x36b00000
	s_addc_u32 s9, s81, 0
	s_cmp_lg_u64 s[10:11], 0
	s_cbranch_scc1 .Lmy_w3_fast
	s_cselect_b64 s[2:3], -1, 0
	v_cndmask_b32_e64 v1, 0, 1, s[2:3]
	s_mov_b64 s[18:19], 0
	v_cmp_ne_u32_e64 s[4:5], 1, v1
	s_mov_b32 s1, 0x1ffff
	v_mov_b32_e32 v9, v10
	s_branch .LBB0_35

.Lmy_w3_fast:
	s_mov_b64 s[18:19], 0
	s_mov_b32 s1, 0x1ffff
	s_mov_b32 s28, 0x1000
	s_mov_b32 s29, 0
	v_mov_b32_e32 v9, v10
.Lmy_w3_loop:
	v_ashrrev_i32_e32 v1, 31, v9
	v_lshrrev_b32_e32 v1, 22, v1
	v_add_u32_e32 v1, v9, v1
	v_ashrrev_i32_e32 v1, 10, v1
	v_mul_i32_i24_e32 v2, 0x400, v1
	v_sub_u32_e32 v14, v9, v2
	v_lshlrev_b32_e32 v12, 3, v1
	v_ashrrev_i32_e32 v15, 31, v14
	v_ashrrev_i32_e32 v13, 31, v12
	v_lshl_add_u64 v[16:17], v[14:15], 2, s[12:13]
	v_lshlrev_b64 v[2:3], 12, v[12:13]
	v_lshl_add_u64 v[2:3], v[16:17], 0, v[2:3]
	v_lshl_add_u64 v[18:19], v[12:13], 2, s[10:11]
	global_load_dword v26, v[2:3], off
	v_lshl_add_u64 v[2:3], v[2:3], 0, s[28:29]
	global_load_dword v27, v[2:3], off
	v_lshl_add_u64 v[2:3], v[2:3], 0, s[28:29]
	global_load_dword v28, v[2:3], off
	v_lshl_add_u64 v[2:3], v[2:3], 0, s[28:29]
	global_load_dword v29, v[2:3], off
	v_lshl_add_u64 v[2:3], v[2:3], 0, s[28:29]
	global_load_dword v30, v[2:3], off
	v_lshl_add_u64 v[2:3], v[2:3], 0, s[28:29]
	global_load_dword v31, v[2:3], off
	v_lshl_add_u64 v[2:3], v[2:3], 0, s[28:29]
	global_load_dword v32, v[2:3], off
	v_lshl_add_u64 v[2:3], v[2:3], 0, s[28:29]
	global_load_dword v33, v[2:3], off
	global_load_dwordx4 v[34:37], v[18:19], off
	global_load_dwordx4 v[38:41], v[18:19], off offset:16
	v_lshlrev_b64 v[6:7], 11, v[14:15]
	v_add_u32_e32 v9, s0, v9
	v_lshl_add_u64 v[6:7], s[8:9], 0, v[6:7]
	v_cmp_lt_i32_e32 vcc, s1, v9
	v_lshl_add_u64 v[6:7], v[12:13], 1, v[6:7]
	s_or_b64 s[18:19], vcc, s[18:19]
	s_waitcnt vmcnt(0)
	v_mul_f32_e32 v26, v26, v34
	v_mul_f32_e32 v27, v27, v35
	v_mul_f32_e32 v28, v28, v36
	v_mul_f32_e32 v29, v29, v37
	v_mul_f32_e32 v30, v30, v38
	v_mul_f32_e32 v31, v31, v39
	v_mul_f32_e32 v32, v32, v40
	v_mul_f32_e32 v33, v33, v41
	v_cvt_pk_bf16_f32 v2, v26, v27
	v_cvt_pk_bf16_f32 v3, v28, v29
	v_cvt_pk_bf16_f32 v4, v30, v31
	v_cvt_pk_bf16_f32 v5, v32, v33
	global_store_dwordx4 v[6:7], v[2:5], off
	s_andn2_b64 exec, exec, s[18:19]
	s_cbranch_execnz .Lmy_w3_loop
	s_branch .LBB0_51
